# phase 1 filter generation rewritten by hand: 4 position tiles of loads kept in flight ahead of the MFMAs and stores
# baseline (speedup 1.0000x reference)
; #define MFMA16(a, b, c) __builtin_amdgcn_mfma_f32_16x16x32_bf16((a), (b), (c), 0, 0, 0)
; DI void phase_pre(const P& p, int bid, int nb) {
;     ...
;     const int fr = lane & 15, fq = lane >> 4;
;     const bf16_t* HDN = (const bf16_t*)(p.ws + OFF_HDN); float* HT = (float*)(p.ws + OFF_HT);
;     for (int id = bid * 8 + wid; id < 128 * 64; id += nb * 8) {
;       const int mt = id & 127, ng = id >> 7; const int ch = mt * 16 + fr;
;       bf16x8 a[2];
; #pragma unroll
;       for (int s = 0; s < 2; ++s)
; #pragma unroll
;         for (int i = 0; i < 8; ++i) a[s][i] = (short)f2bf(p.out_w[(size_t)(s * 32 + fq * 8 + i) * 2048 + ch]);
;       const float lo = -120.39728043259361f, hi = 40.546510810816436f;
;       const float delta = fabsf(lo + (float)(ch & 1023) * ((hi - lo) / 1023.f));
;       for (int q = 0; q < 16; ++q) {
;         const int n0 = (ng * 16 + q) * 16;
;         bf16x8 b0 = *(const bf16x8*)(HDN + (size_t)(n0 + fr) * 64 + fq * 8), b1 = *(const bf16x8*)(HDN + (size_t)(n0 + fr) * 64 + 32 + fq * 8);
;         f32x4 acc = {0, 0, 0, 0};
;         acc = MFMA16(b0, a[0], acc); acc = MFMA16(b1, a[1], acc);
; #pragma unroll
;         for (int jj = 0; jj < 4; ++jj) { float tl = (float)(n0 + 4 * fq + jj) * (1.f / 16383.f); acc[jj] *= __expf(-tl * delta); }
;         *(f32x4*)(HT + (size_t)ch * 16384 + n0 + 4 * fq) = acc;
.LBB0_64:
	s_or_b64 exec, exec, s[4:5]
	v_and_b32_e32 v1, 0x3ff, v0
	v_lshrrev_b32_e32 v3, 6, v1
	v_and_b32_e32 v4, 63, v1
	v_and_b32_e32 v5, 15, v4
	v_readfirstlane_b32 s3, v3
	v_lshrrev_b32_e32 v6, 4, v4
	s_lshl_b32 s6, s2, 3
	s_add_u32 s3, s3, s6
	s_lshl_b32 s7, s88, 3
	v_lshlrev_b32_e32 v7, 16, v6
	v_lshl_add_u32 v7, v5, 2, v7
	v_lshlrev_b32_e32 v8, 7, v5
	v_lshl_add_u32 v8, v6, 4, v8
	v_lshlrev_b32_e32 v9, 16, v5
	v_lshl_add_u32 v9, v6, 4, v9
	v_lshlrev_b32_e32 v10, 2, v6
	v_mov_b32_e32 v13, 0xc2f0cb68
	v_readlane_b32 s30, v254, 14
	v_readlane_b32 s31, v254, 15
	s_movk_i32 s14, 0x2000
	s_cmp_ge_i32 s3, s14
	s_cbranch_scc1 .Lfg_done
.Lfg_id:
	s_and_b32 s8, s3, 0x7f
	s_lshr_b32 s9, s3, 7
	s_lshl_b32 s12, s8, 6
	s_add_u32 s10, s30, s12
	s_addc_u32 s11, s31, 0
	global_load_dword v16, v7, s[10:11]
	s_add_u32 s10, s10, 0x2000
	s_addc_u32 s11, s11, 0
	global_load_dword v17, v7, s[10:11]
	s_add_u32 s10, s10, 0x2000
	s_addc_u32 s11, s11, 0
	global_load_dword v18, v7, s[10:11]
	s_add_u32 s10, s10, 0x2000
	s_addc_u32 s11, s11, 0
	global_load_dword v19, v7, s[10:11]
	s_add_u32 s10, s10, 0x2000
	s_addc_u32 s11, s11, 0
	global_load_dword v20, v7, s[10:11]
	s_add_u32 s10, s10, 0x2000
	s_addc_u32 s11, s11, 0
	global_load_dword v21, v7, s[10:11]
	s_add_u32 s10, s10, 0x2000
	s_addc_u32 s11, s11, 0
	global_load_dword v22, v7, s[10:11]
	s_add_u32 s10, s10, 0x2000
	s_addc_u32 s11, s11, 0
	global_load_dword v23, v7, s[10:11]
	s_add_u32 s10, s10, 0x32000
	s_addc_u32 s11, s11, 0
	global_load_dword v24, v7, s[10:11]
	s_add_u32 s10, s10, 0x2000
	s_addc_u32 s11, s11, 0
	global_load_dword v25, v7, s[10:11]
	s_add_u32 s10, s10, 0x2000
	s_addc_u32 s11, s11, 0
	global_load_dword v26, v7, s[10:11]
	s_add_u32 s10, s10, 0x2000
	s_addc_u32 s11, s11, 0
	global_load_dword v27, v7, s[10:11]
	s_add_u32 s10, s10, 0x2000
	s_addc_u32 s11, s11, 0
	global_load_dword v28, v7, s[10:11]
	s_add_u32 s10, s10, 0x2000
	s_addc_u32 s11, s11, 0
	global_load_dword v29, v7, s[10:11]
	s_add_u32 s10, s10, 0x2000
	s_addc_u32 s11, s11, 0
	global_load_dword v30, v7, s[10:11]
	s_add_u32 s10, s10, 0x2000
	s_addc_u32 s11, s11, 0
	global_load_dword v31, v7, s[10:11]
	s_lshl_b32 s12, s8, 4
	s_and_b32 s12, s12, 0x3ff
	v_or_b32_e32 v11, s12, v5
	v_cvt_f32_u32_e32 v11, v11
	v_fmamk_f32 v11, v11, 0x3e2119e2, v13
	s_lshl_b32 s12, s9, 8
	v_add_u32_e32 v12, s12, v10
	s_lshl_b32 s12, s9, 15
	s_add_u32 s16, s84, s12
	s_addc_u32 s17, s85, 0
	s_add_u32 s16, s16, 0x100000
	s_addc_u32 s17, s17, 0
	s_lshl_b32 s12, s8, 20
	s_lshl_b32 s13, s9, 10
	s_add_u32 s12, s12, s13
	s_add_u32 s18, s84, s12
	s_addc_u32 s19, s85, 0
	s_add_u32 s18, s18, 0xbb00000
	s_addc_u32 s19, s19, 0
	s_add_u32 s20, s16, 0x1000
	s_addc_u32 s21, s17, 0
	global_load_dwordx4 v[32:35], v8, s[16:17]
	global_load_dwordx4 v[36:39], v8, s[16:17] offset:64
	global_load_dwordx4 v[40:43], v8, s[16:17] offset:2048
	global_load_dwordx4 v[44:47], v8, s[16:17] offset:2112
	global_load_dwordx4 v[48:51], v8, s[20:21]
	global_load_dwordx4 v[52:55], v8, s[20:21] offset:64
	global_load_dwordx4 v[56:59], v8, s[20:21] offset:2048
	global_load_dwordx4 v[60:63], v8, s[20:21] offset:2112
	s_add_u32 s16, s16, 0x2000
	s_addc_u32 s17, s17, 0
	s_waitcnt vmcnt(8)
	v_cvt_pk_bf16_f32 v64, v16, v17
	v_cvt_pk_bf16_f32 v65, v18, v19
	v_cvt_pk_bf16_f32 v66, v20, v21
	v_cvt_pk_bf16_f32 v67, v22, v23
	v_cvt_pk_bf16_f32 v68, v24, v25
	v_cvt_pk_bf16_f32 v69, v26, v27
	v_cvt_pk_bf16_f32 v70, v28, v29
	v_cvt_pk_bf16_f32 v71, v30, v31
	s_add_u32 s20, s16, 0x1000
	s_addc_u32 s21, s17, 0
	global_load_dwordx4 v[72:75], v8, s[16:17]
	global_load_dwordx4 v[76:79], v8, s[16:17] offset:64
	global_load_dwordx4 v[80:83], v8, s[16:17] offset:2048
	global_load_dwordx4 v[84:87], v8, s[16:17] offset:2112
	global_load_dwordx4 v[88:91], v8, s[20:21]
	global_load_dwordx4 v[92:95], v8, s[20:21] offset:64
	global_load_dwordx4 v[96:99], v8, s[20:21] offset:2048
	global_load_dwordx4 v[100:103], v8, s[20:21] offset:2112
	s_add_u32 s16, s16, 0x2000
	s_addc_u32 s17, s17, 0
	s_waitcnt vmcnt(8)
	v_add_u32_e32 v108, 0, v12
	v_add_u32_e32 v109, 1, v12
	v_add_u32_e32 v110, 2, v12
	v_add_u32_e32 v111, 3, v12
	v_cvt_f32_i32_e32 v108, v108
	v_cvt_f32_i32_e32 v109, v109
	v_cvt_f32_i32_e32 v110, v110
	v_cvt_f32_i32_e32 v111, v111
	v_mul_f32_e32 v108, 0xb8800200, v108
	v_mul_f32_e32 v109, 0xb8800200, v109
	v_mul_f32_e32 v110, 0xb8800200, v110
	v_mul_f32_e32 v111, 0xb8800200, v111
	v_mul_f32_e64 v108, |v11|, v108
	v_mul_f32_e64 v109, |v11|, v109
	v_mul_f32_e64 v110, |v11|, v110
	v_mul_f32_e64 v111, |v11|, v111
	v_mul_f32_e32 v108, 0x3fb8aa3b, v108
	v_mul_f32_e32 v109, 0x3fb8aa3b, v109
	v_mul_f32_e32 v110, 0x3fb8aa3b, v110
	v_mul_f32_e32 v111, 0x3fb8aa3b, v111
	v_mfma_f32_16x16x32_bf16 v[32:35], v[32:35], v[64:67], 0
	v_mfma_f32_16x16x32_bf16 v[32:35], v[36:39], v[68:71], v[32:35]
	v_exp_f32_e32 v104, v108
	v_exp_f32_e32 v105, v109
	v_exp_f32_e32 v106, v110
	v_exp_f32_e32 v107, v111
	s_nop 7
	v_pk_mul_f32 v[34:35], v[34:35], v[106:107]
	v_pk_mul_f32 v[32:33], v[32:33], v[104:105]
	global_store_dwordx4 v9, v[32:35], s[18:19]
	v_add_u32_e32 v108, 16, v12
	v_add_u32_e32 v109, 17, v12
	v_add_u32_e32 v110, 18, v12
	v_add_u32_e32 v111, 19, v12
	v_cvt_f32_i32_e32 v108, v108
	v_cvt_f32_i32_e32 v109, v109
	v_cvt_f32_i32_e32 v110, v110
	v_cvt_f32_i32_e32 v111, v111
	v_mul_f32_e32 v108, 0xb8800200, v108
	v_mul_f32_e32 v109, 0xb8800200, v109
	v_mul_f32_e32 v110, 0xb8800200, v110
	v_mul_f32_e32 v111, 0xb8800200, v111
	v_mul_f32_e64 v108, |v11|, v108
	v_mul_f32_e64 v109, |v11|, v109
	v_mul_f32_e64 v110, |v11|, v110
	v_mul_f32_e64 v111, |v11|, v111
	v_mul_f32_e32 v108, 0x3fb8aa3b, v108
	v_mul_f32_e32 v109, 0x3fb8aa3b, v109
; #define MFMA16(a, b, c) __builtin_amdgcn_mfma_f32_16x16x32_bf16((a), (b), (c), 0, 0, 0)
; DI void phase_pre(const P& p, int bid, int nb) {
;     ...
;       for (int q = 0; q < 16; ++q) {
;         const int n0 = (ng * 16 + q) * 16;
;         bf16x8 b0 = *(const bf16x8*)(HDN + (size_t)(n0 + fr) * 64 + fq * 8), b1 = *(const bf16x8*)(HDN + (size_t)(n0 + fr) * 64 + 32 + fq * 8);
;         f32x4 acc = {0, 0, 0, 0};
;         acc = MFMA16(b0, a[0], acc); acc = MFMA16(b1, a[1], acc);
; #pragma unroll
;         for (int jj = 0; jj < 4; ++jj) { float tl = (float)(n0 + 4 * fq + jj) * (1.f / 16383.f); acc[jj] *= __expf(-tl * delta); }
;         *(f32x4*)(HT + (size_t)ch * 16384 + n0 + 4 * fq) = acc;
	v_mul_f32_e32 v110, 0x3fb8aa3b, v110
	v_mul_f32_e32 v111, 0x3fb8aa3b, v111
	v_mfma_f32_16x16x32_bf16 v[40:43], v[40:43], v[64:67], 0
	v_mfma_f32_16x16x32_bf16 v[40:43], v[44:47], v[68:71], v[40:43]
	v_exp_f32_e32 v104, v108
	v_exp_f32_e32 v105, v109
	v_exp_f32_e32 v106, v110
	v_exp_f32_e32 v107, v111
	s_nop 7
	v_pk_mul_f32 v[42:43], v[42:43], v[106:107]
	v_pk_mul_f32 v[40:41], v[40:41], v[104:105]
	global_store_dwordx4 v9, v[40:43], s[18:19] offset:64
	v_add_u32_e32 v108, 32, v12
	v_add_u32_e32 v109, 33, v12
	v_add_u32_e32 v110, 34, v12
	v_add_u32_e32 v111, 35, v12
	v_cvt_f32_i32_e32 v108, v108
	v_cvt_f32_i32_e32 v109, v109
	v_cvt_f32_i32_e32 v110, v110
	v_cvt_f32_i32_e32 v111, v111
	v_mul_f32_e32 v108, 0xb8800200, v108
	v_mul_f32_e32 v109, 0xb8800200, v109
	v_mul_f32_e32 v110, 0xb8800200, v110
	v_mul_f32_e32 v111, 0xb8800200, v111
	v_mul_f32_e64 v108, |v11|, v108
	v_mul_f32_e64 v109, |v11|, v109
	v_mul_f32_e64 v110, |v11|, v110
	v_mul_f32_e64 v111, |v11|, v111
	v_mul_f32_e32 v108, 0x3fb8aa3b, v108
	v_mul_f32_e32 v109, 0x3fb8aa3b, v109
	v_mul_f32_e32 v110, 0x3fb8aa3b, v110
	v_mul_f32_e32 v111, 0x3fb8aa3b, v111
	v_mfma_f32_16x16x32_bf16 v[48:51], v[48:51], v[64:67], 0
	v_mfma_f32_16x16x32_bf16 v[48:51], v[52:55], v[68:71], v[48:51]
	v_exp_f32_e32 v104, v108
	v_exp_f32_e32 v105, v109
	v_exp_f32_e32 v106, v110
	v_exp_f32_e32 v107, v111
	s_nop 7
	v_pk_mul_f32 v[50:51], v[50:51], v[106:107]
	v_pk_mul_f32 v[48:49], v[48:49], v[104:105]
	global_store_dwordx4 v9, v[48:51], s[18:19] offset:128
	v_add_u32_e32 v108, 48, v12
	v_add_u32_e32 v109, 49, v12
	v_add_u32_e32 v110, 50, v12
	v_add_u32_e32 v111, 51, v12
	v_cvt_f32_i32_e32 v108, v108
	v_cvt_f32_i32_e32 v109, v109
	v_cvt_f32_i32_e32 v110, v110
	v_cvt_f32_i32_e32 v111, v111
	v_mul_f32_e32 v108, 0xb8800200, v108
	v_mul_f32_e32 v109, 0xb8800200, v109
	v_mul_f32_e32 v110, 0xb8800200, v110
	v_mul_f32_e32 v111, 0xb8800200, v111
	v_mul_f32_e64 v108, |v11|, v108
	v_mul_f32_e64 v109, |v11|, v109
	v_mul_f32_e64 v110, |v11|, v110
	v_mul_f32_e64 v111, |v11|, v111
	v_mul_f32_e32 v108, 0x3fb8aa3b, v108
	v_mul_f32_e32 v109, 0x3fb8aa3b, v109
	v_mul_f32_e32 v110, 0x3fb8aa3b, v110
	v_mul_f32_e32 v111, 0x3fb8aa3b, v111
	v_mfma_f32_16x16x32_bf16 v[56:59], v[56:59], v[64:67], 0
	v_mfma_f32_16x16x32_bf16 v[56:59], v[60:63], v[68:71], v[56:59]
	v_exp_f32_e32 v104, v108
	v_exp_f32_e32 v105, v109
	v_exp_f32_e32 v106, v110
	v_exp_f32_e32 v107, v111
	s_nop 7
	v_pk_mul_f32 v[58:59], v[58:59], v[106:107]
	v_pk_mul_f32 v[56:57], v[56:57], v[104:105]
	global_store_dwordx4 v9, v[56:59], s[18:19] offset:192
	s_add_u32 s20, s16, 0x1000
	s_addc_u32 s21, s17, 0
	global_load_dwordx4 v[32:35], v8, s[16:17]
	global_load_dwordx4 v[36:39], v8, s[16:17] offset:64
	global_load_dwordx4 v[40:43], v8, s[16:17] offset:2048
	global_load_dwordx4 v[44:47], v8, s[16:17] offset:2112
	global_load_dwordx4 v[48:51], v8, s[20:21]
	global_load_dwordx4 v[52:55], v8, s[20:21] offset:64
	global_load_dwordx4 v[56:59], v8, s[20:21] offset:2048
	global_load_dwordx4 v[60:63], v8, s[20:21] offset:2112
	s_add_u32 s16, s16, 0x2000
	s_addc_u32 s17, s17, 0
	s_waitcnt vmcnt(12)
	v_add_u32_e32 v108, 64, v12
	v_add_u32_e32 v109, 65, v12
	v_add_u32_e32 v110, 66, v12
	v_add_u32_e32 v111, 67, v12
	v_cvt_f32_i32_e32 v108, v108
	v_cvt_f32_i32_e32 v109, v109
	v_cvt_f32_i32_e32 v110, v110
	v_cvt_f32_i32_e32 v111, v111
	v_mul_f32_e32 v108, 0xb8800200, v108
	v_mul_f32_e32 v109, 0xb8800200, v109
	v_mul_f32_e32 v110, 0xb8800200, v110
	v_mul_f32_e32 v111, 0xb8800200, v111
	v_mul_f32_e64 v108, |v11|, v108
	v_mul_f32_e64 v109, |v11|, v109
	v_mul_f32_e64 v110, |v11|, v110
	v_mul_f32_e64 v111, |v11|, v111
	v_mul_f32_e32 v108, 0x3fb8aa3b, v108
	v_mul_f32_e32 v109, 0x3fb8aa3b, v109
	v_mul_f32_e32 v110, 0x3fb8aa3b, v110
	v_mul_f32_e32 v111, 0x3fb8aa3b, v111
	v_mfma_f32_16x16x32_bf16 v[72:75], v[72:75], v[64:67], 0
	v_mfma_f32_16x16x32_bf16 v[72:75], v[76:79], v[68:71], v[72:75]
	v_exp_f32_e32 v104, v108
	v_exp_f32_e32 v105, v109
	v_exp_f32_e32 v106, v110
	v_exp_f32_e32 v107, v111
	s_nop 7
	v_pk_mul_f32 v[74:75], v[74:75], v[106:107]
	v_pk_mul_f32 v[72:73], v[72:73], v[104:105]
	global_store_dwordx4 v9, v[72:75], s[18:19] offset:256
	v_add_u32_e32 v108, 80, v12
	v_add_u32_e32 v109, 81, v12
	v_add_u32_e32 v110, 82, v12
	v_add_u32_e32 v111, 83, v12
	v_cvt_f32_i32_e32 v108, v108
	v_cvt_f32_i32_e32 v109, v109
	v_cvt_f32_i32_e32 v110, v110
	v_cvt_f32_i32_e32 v111, v111
	v_mul_f32_e32 v108, 0xb8800200, v108
	v_mul_f32_e32 v109, 0xb8800200, v109
	v_mul_f32_e32 v110, 0xb8800200, v110
	v_mul_f32_e32 v111, 0xb8800200, v111
	v_mul_f32_e64 v108, |v11|, v108
	v_mul_f32_e64 v109, |v11|, v109
	v_mul_f32_e64 v110, |v11|, v110
	v_mul_f32_e64 v111, |v11|, v111
	v_mul_f32_e32 v108, 0x3fb8aa3b, v108
	v_mul_f32_e32 v109, 0x3fb8aa3b, v109
	v_mul_f32_e32 v110, 0x3fb8aa3b, v110
	v_mul_f32_e32 v111, 0x3fb8aa3b, v111
	v_mfma_f32_16x16x32_bf16 v[80:83], v[80:83], v[64:67], 0
	v_mfma_f32_16x16x32_bf16 v[80:83], v[84:87], v[68:71], v[80:83]
	v_exp_f32_e32 v104, v108
	v_exp_f32_e32 v105, v109
	v_exp_f32_e32 v106, v110
	v_exp_f32_e32 v107, v111
	s_nop 7
	v_pk_mul_f32 v[82:83], v[82:83], v[106:107]
	v_pk_mul_f32 v[80:81], v[80:81], v[104:105]
	global_store_dwordx4 v9, v[80:83], s[18:19] offset:320
	v_add_u32_e32 v108, 96, v12
	v_add_u32_e32 v109, 97, v12
	v_add_u32_e32 v110, 98, v12
	v_add_u32_e32 v111, 99, v12
	v_cvt_f32_i32_e32 v108, v108
	v_cvt_f32_i32_e32 v109, v109
	v_cvt_f32_i32_e32 v110, v110
	v_cvt_f32_i32_e32 v111, v111
	v_mul_f32_e32 v108, 0xb8800200, v108
	v_mul_f32_e32 v109, 0xb8800200, v109
	v_mul_f32_e32 v110, 0xb8800200, v110
	v_mul_f32_e32 v111, 0xb8800200, v111
	v_mul_f32_e64 v108, |v11|, v108
; #define MFMA16(a, b, c) __builtin_amdgcn_mfma_f32_16x16x32_bf16((a), (b), (c), 0, 0, 0)
; DI void phase_pre(const P& p, int bid, int nb) {
;     ...
;       for (int q = 0; q < 16; ++q) {
;         const int n0 = (ng * 16 + q) * 16;
;         bf16x8 b0 = *(const bf16x8*)(HDN + (size_t)(n0 + fr) * 64 + fq * 8), b1 = *(const bf16x8*)(HDN + (size_t)(n0 + fr) * 64 + 32 + fq * 8);
;         f32x4 acc = {0, 0, 0, 0};
;         acc = MFMA16(b0, a[0], acc); acc = MFMA16(b1, a[1], acc);
; #pragma unroll
;         for (int jj = 0; jj < 4; ++jj) { float tl = (float)(n0 + 4 * fq + jj) * (1.f / 16383.f); acc[jj] *= __expf(-tl * delta); }
;         *(f32x4*)(HT + (size_t)ch * 16384 + n0 + 4 * fq) = acc;
	v_mul_f32_e64 v109, |v11|, v109
	v_mul_f32_e64 v110, |v11|, v110
	v_mul_f32_e64 v111, |v11|, v111
	v_mul_f32_e32 v108, 0x3fb8aa3b, v108
	v_mul_f32_e32 v109, 0x3fb8aa3b, v109
	v_mul_f32_e32 v110, 0x3fb8aa3b, v110
	v_mul_f32_e32 v111, 0x3fb8aa3b, v111
	v_mfma_f32_16x16x32_bf16 v[88:91], v[88:91], v[64:67], 0
	v_mfma_f32_16x16x32_bf16 v[88:91], v[92:95], v[68:71], v[88:91]
	v_exp_f32_e32 v104, v108
	v_exp_f32_e32 v105, v109
	v_exp_f32_e32 v106, v110
	v_exp_f32_e32 v107, v111
	s_nop 7
	v_pk_mul_f32 v[90:91], v[90:91], v[106:107]
	v_pk_mul_f32 v[88:89], v[88:89], v[104:105]
	global_store_dwordx4 v9, v[88:91], s[18:19] offset:384
	v_add_u32_e32 v108, 112, v12
	v_add_u32_e32 v109, 113, v12
	v_add_u32_e32 v110, 114, v12
	v_add_u32_e32 v111, 115, v12
	v_cvt_f32_i32_e32 v108, v108
	v_cvt_f32_i32_e32 v109, v109
	v_cvt_f32_i32_e32 v110, v110
	v_cvt_f32_i32_e32 v111, v111
	v_mul_f32_e32 v108, 0xb8800200, v108
	v_mul_f32_e32 v109, 0xb8800200, v109
	v_mul_f32_e32 v110, 0xb8800200, v110
	v_mul_f32_e32 v111, 0xb8800200, v111
	v_mul_f32_e64 v108, |v11|, v108
	v_mul_f32_e64 v109, |v11|, v109
	v_mul_f32_e64 v110, |v11|, v110
	v_mul_f32_e64 v111, |v11|, v111
	v_mul_f32_e32 v108, 0x3fb8aa3b, v108
	v_mul_f32_e32 v109, 0x3fb8aa3b, v109
	v_mul_f32_e32 v110, 0x3fb8aa3b, v110
	v_mul_f32_e32 v111, 0x3fb8aa3b, v111
	v_mfma_f32_16x16x32_bf16 v[96:99], v[96:99], v[64:67], 0
	v_mfma_f32_16x16x32_bf16 v[96:99], v[100:103], v[68:71], v[96:99]
	v_exp_f32_e32 v104, v108
	v_exp_f32_e32 v105, v109
	v_exp_f32_e32 v106, v110
	v_exp_f32_e32 v107, v111
	s_nop 7
	v_pk_mul_f32 v[98:99], v[98:99], v[106:107]
	v_pk_mul_f32 v[96:97], v[96:97], v[104:105]
	global_store_dwordx4 v9, v[96:99], s[18:19] offset:448
	s_add_u32 s20, s16, 0x1000
	s_addc_u32 s21, s17, 0
	global_load_dwordx4 v[72:75], v8, s[16:17]
	global_load_dwordx4 v[76:79], v8, s[16:17] offset:64
	global_load_dwordx4 v[80:83], v8, s[16:17] offset:2048
	global_load_dwordx4 v[84:87], v8, s[16:17] offset:2112
	global_load_dwordx4 v[88:91], v8, s[20:21]
	global_load_dwordx4 v[92:95], v8, s[20:21] offset:64
	global_load_dwordx4 v[96:99], v8, s[20:21] offset:2048
	global_load_dwordx4 v[100:103], v8, s[20:21] offset:2112
	s_add_u32 s16, s16, 0x2000
	s_addc_u32 s17, s17, 0
	s_waitcnt vmcnt(12)
	v_add_u32_e32 v108, 128, v12
	v_add_u32_e32 v109, 129, v12
	v_add_u32_e32 v110, 130, v12
	v_add_u32_e32 v111, 131, v12
	v_cvt_f32_i32_e32 v108, v108
	v_cvt_f32_i32_e32 v109, v109
	v_cvt_f32_i32_e32 v110, v110
	v_cvt_f32_i32_e32 v111, v111
	v_mul_f32_e32 v108, 0xb8800200, v108
	v_mul_f32_e32 v109, 0xb8800200, v109
	v_mul_f32_e32 v110, 0xb8800200, v110
	v_mul_f32_e32 v111, 0xb8800200, v111
	v_mul_f32_e64 v108, |v11|, v108
	v_mul_f32_e64 v109, |v11|, v109
	v_mul_f32_e64 v110, |v11|, v110
	v_mul_f32_e64 v111, |v11|, v111
	v_mul_f32_e32 v108, 0x3fb8aa3b, v108
	v_mul_f32_e32 v109, 0x3fb8aa3b, v109
	v_mul_f32_e32 v110, 0x3fb8aa3b, v110
	v_mul_f32_e32 v111, 0x3fb8aa3b, v111
	v_mfma_f32_16x16x32_bf16 v[32:35], v[32:35], v[64:67], 0
	v_mfma_f32_16x16x32_bf16 v[32:35], v[36:39], v[68:71], v[32:35]
	v_exp_f32_e32 v104, v108
	v_exp_f32_e32 v105, v109
	v_exp_f32_e32 v106, v110
	v_exp_f32_e32 v107, v111
	s_nop 7
	v_pk_mul_f32 v[34:35], v[34:35], v[106:107]
	v_pk_mul_f32 v[32:33], v[32:33], v[104:105]
	global_store_dwordx4 v9, v[32:35], s[18:19] offset:512
	v_add_u32_e32 v108, 144, v12
	v_add_u32_e32 v109, 145, v12
	v_add_u32_e32 v110, 146, v12
	v_add_u32_e32 v111, 147, v12
	v_cvt_f32_i32_e32 v108, v108
	v_cvt_f32_i32_e32 v109, v109
	v_cvt_f32_i32_e32 v110, v110
	v_cvt_f32_i32_e32 v111, v111
	v_mul_f32_e32 v108, 0xb8800200, v108
	v_mul_f32_e32 v109, 0xb8800200, v109
	v_mul_f32_e32 v110, 0xb8800200, v110
	v_mul_f32_e32 v111, 0xb8800200, v111
	v_mul_f32_e64 v108, |v11|, v108
	v_mul_f32_e64 v109, |v11|, v109
	v_mul_f32_e64 v110, |v11|, v110
	v_mul_f32_e64 v111, |v11|, v111
	v_mul_f32_e32 v108, 0x3fb8aa3b, v108
	v_mul_f32_e32 v109, 0x3fb8aa3b, v109
	v_mul_f32_e32 v110, 0x3fb8aa3b, v110
	v_mul_f32_e32 v111, 0x3fb8aa3b, v111
	v_mfma_f32_16x16x32_bf16 v[40:43], v[40:43], v[64:67], 0
	v_mfma_f32_16x16x32_bf16 v[40:43], v[44:47], v[68:71], v[40:43]
	v_exp_f32_e32 v104, v108
	v_exp_f32_e32 v105, v109
	v_exp_f32_e32 v106, v110
	v_exp_f32_e32 v107, v111
	s_nop 7
	v_pk_mul_f32 v[42:43], v[42:43], v[106:107]
	v_pk_mul_f32 v[40:41], v[40:41], v[104:105]
	global_store_dwordx4 v9, v[40:43], s[18:19] offset:576
	v_add_u32_e32 v108, 160, v12
	v_add_u32_e32 v109, 161, v12
	v_add_u32_e32 v110, 162, v12
	v_add_u32_e32 v111, 163, v12
	v_cvt_f32_i32_e32 v108, v108
	v_cvt_f32_i32_e32 v109, v109
	v_cvt_f32_i32_e32 v110, v110
	v_cvt_f32_i32_e32 v111, v111
	v_mul_f32_e32 v108, 0xb8800200, v108
	v_mul_f32_e32 v109, 0xb8800200, v109
	v_mul_f32_e32 v110, 0xb8800200, v110
	v_mul_f32_e32 v111, 0xb8800200, v111
	v_mul_f32_e64 v108, |v11|, v108
	v_mul_f32_e64 v109, |v11|, v109
	v_mul_f32_e64 v110, |v11|, v110
	v_mul_f32_e64 v111, |v11|, v111
	v_mul_f32_e32 v108, 0x3fb8aa3b, v108
	v_mul_f32_e32 v109, 0x3fb8aa3b, v109
	v_mul_f32_e32 v110, 0x3fb8aa3b, v110
	v_mul_f32_e32 v111, 0x3fb8aa3b, v111
	v_mfma_f32_16x16x32_bf16 v[48:51], v[48:51], v[64:67], 0
	v_mfma_f32_16x16x32_bf16 v[48:51], v[52:55], v[68:71], v[48:51]
	v_exp_f32_e32 v104, v108
	v_exp_f32_e32 v105, v109
	v_exp_f32_e32 v106, v110
	v_exp_f32_e32 v107, v111
	s_nop 7
	v_pk_mul_f32 v[50:51], v[50:51], v[106:107]
	v_pk_mul_f32 v[48:49], v[48:49], v[104:105]
	global_store_dwordx4 v9, v[48:51], s[18:19] offset:640
	v_add_u32_e32 v108, 176, v12
	v_add_u32_e32 v109, 177, v12
	v_add_u32_e32 v110, 178, v12
	v_add_u32_e32 v111, 179, v12
	v_cvt_f32_i32_e32 v108, v108
	v_cvt_f32_i32_e32 v109, v109
	v_cvt_f32_i32_e32 v110, v110
	v_cvt_f32_i32_e32 v111, v111
	v_mul_f32_e32 v108, 0xb8800200, v108
	v_mul_f32_e32 v109, 0xb8800200, v109
	v_mul_f32_e32 v110, 0xb8800200, v110
	v_mul_f32_e32 v111, 0xb8800200, v111
	v_mul_f32_e64 v108, |v11|, v108
	v_mul_f32_e64 v109, |v11|, v109
	v_mul_f32_e64 v110, |v11|, v110
	v_mul_f32_e64 v111, |v11|, v111
	v_mul_f32_e32 v108, 0x3fb8aa3b, v108
	v_mul_f32_e32 v109, 0x3fb8aa3b, v109
	v_mul_f32_e32 v110, 0x3fb8aa3b, v110
	v_mul_f32_e32 v111, 0x3fb8aa3b, v111
	v_mfma_f32_16x16x32_bf16 v[56:59], v[56:59], v[64:67], 0
	v_mfma_f32_16x16x32_bf16 v[56:59], v[60:63], v[68:71], v[56:59]
	v_exp_f32_e32 v104, v108
	v_exp_f32_e32 v105, v109
	v_exp_f32_e32 v106, v110
	v_exp_f32_e32 v107, v111
	s_nop 7
	v_pk_mul_f32 v[58:59], v[58:59], v[106:107]
	v_pk_mul_f32 v[56:57], v[56:57], v[104:105]
	global_store_dwordx4 v9, v[56:59], s[18:19] offset:704
	s_waitcnt vmcnt(4)
; #define MFMA16(a, b, c) __builtin_amdgcn_mfma_f32_16x16x32_bf16((a), (b), (c), 0, 0, 0)
; DI void phase_pre(const P& p, int bid, int nb) {
;     ...
;     for (int id = bid * 8 + wid; id < 128 * 64; id += nb * 8) {
;       const int mt = id & 127, ng = id >> 7; const int ch = mt * 16 + fr;
;       bf16x8 a[2];
; #pragma unroll
;       for (int s = 0; s < 2; ++s)
; #pragma unroll
;         for (int i = 0; i < 8; ++i) a[s][i] = (short)f2bf(p.out_w[(size_t)(s * 32 + fq * 8 + i) * 2048 + ch]);
;       const float lo = -120.39728043259361f, hi = 40.546510810816436f;
;       const float delta = fabsf(lo + (float)(ch & 1023) * ((hi - lo) / 1023.f));
;       for (int q = 0; q < 16; ++q) {
;         const int n0 = (ng * 16 + q) * 16;
;         bf16x8 b0 = *(const bf16x8*)(HDN + (size_t)(n0 + fr) * 64 + fq * 8), b1 = *(const bf16x8*)(HDN + (size_t)(n0 + fr) * 64 + 32 + fq * 8);
;         f32x4 acc = {0, 0, 0, 0};
;         acc = MFMA16(b0, a[0], acc); acc = MFMA16(b1, a[1], acc);
; #pragma unroll
;         for (int jj = 0; jj < 4; ++jj) { float tl = (float)(n0 + 4 * fq + jj) * (1.f / 16383.f); acc[jj] *= __expf(-tl * delta); }
;         *(f32x4*)(HT + (size_t)ch * 16384 + n0 + 4 * fq) = acc;
;       }
;     }
	v_add_u32_e32 v108, 192, v12
	v_add_u32_e32 v109, 193, v12
	v_add_u32_e32 v110, 194, v12
	v_add_u32_e32 v111, 195, v12
	v_cvt_f32_i32_e32 v108, v108
	v_cvt_f32_i32_e32 v109, v109
	v_cvt_f32_i32_e32 v110, v110
	v_cvt_f32_i32_e32 v111, v111
	v_mul_f32_e32 v108, 0xb8800200, v108
	v_mul_f32_e32 v109, 0xb8800200, v109
	v_mul_f32_e32 v110, 0xb8800200, v110
	v_mul_f32_e32 v111, 0xb8800200, v111
	v_mul_f32_e64 v108, |v11|, v108
	v_mul_f32_e64 v109, |v11|, v109
	v_mul_f32_e64 v110, |v11|, v110
	v_mul_f32_e64 v111, |v11|, v111
	v_mul_f32_e32 v108, 0x3fb8aa3b, v108
	v_mul_f32_e32 v109, 0x3fb8aa3b, v109
	v_mul_f32_e32 v110, 0x3fb8aa3b, v110
	v_mul_f32_e32 v111, 0x3fb8aa3b, v111
	v_mfma_f32_16x16x32_bf16 v[72:75], v[72:75], v[64:67], 0
	v_mfma_f32_16x16x32_bf16 v[72:75], v[76:79], v[68:71], v[72:75]
	v_exp_f32_e32 v104, v108
	v_exp_f32_e32 v105, v109
	v_exp_f32_e32 v106, v110
	v_exp_f32_e32 v107, v111
	s_nop 7
	v_pk_mul_f32 v[74:75], v[74:75], v[106:107]
	v_pk_mul_f32 v[72:73], v[72:73], v[104:105]
	global_store_dwordx4 v9, v[72:75], s[18:19] offset:768
	v_add_u32_e32 v108, 208, v12
	v_add_u32_e32 v109, 209, v12
	v_add_u32_e32 v110, 210, v12
	v_add_u32_e32 v111, 211, v12
	v_cvt_f32_i32_e32 v108, v108
	v_cvt_f32_i32_e32 v109, v109
	v_cvt_f32_i32_e32 v110, v110
	v_cvt_f32_i32_e32 v111, v111
	v_mul_f32_e32 v108, 0xb8800200, v108
	v_mul_f32_e32 v109, 0xb8800200, v109
	v_mul_f32_e32 v110, 0xb8800200, v110
	v_mul_f32_e32 v111, 0xb8800200, v111
	v_mul_f32_e64 v108, |v11|, v108
	v_mul_f32_e64 v109, |v11|, v109
	v_mul_f32_e64 v110, |v11|, v110
	v_mul_f32_e64 v111, |v11|, v111
	v_mul_f32_e32 v108, 0x3fb8aa3b, v108
	v_mul_f32_e32 v109, 0x3fb8aa3b, v109
	v_mul_f32_e32 v110, 0x3fb8aa3b, v110
	v_mul_f32_e32 v111, 0x3fb8aa3b, v111
	v_mfma_f32_16x16x32_bf16 v[80:83], v[80:83], v[64:67], 0
	v_mfma_f32_16x16x32_bf16 v[80:83], v[84:87], v[68:71], v[80:83]
	v_exp_f32_e32 v104, v108
	v_exp_f32_e32 v105, v109
	v_exp_f32_e32 v106, v110
	v_exp_f32_e32 v107, v111
	s_nop 7
	v_pk_mul_f32 v[82:83], v[82:83], v[106:107]
	v_pk_mul_f32 v[80:81], v[80:81], v[104:105]
	global_store_dwordx4 v9, v[80:83], s[18:19] offset:832
	v_add_u32_e32 v108, 224, v12
	v_add_u32_e32 v109, 225, v12
	v_add_u32_e32 v110, 226, v12
	v_add_u32_e32 v111, 227, v12
	v_cvt_f32_i32_e32 v108, v108
	v_cvt_f32_i32_e32 v109, v109
	v_cvt_f32_i32_e32 v110, v110
	v_cvt_f32_i32_e32 v111, v111
	v_mul_f32_e32 v108, 0xb8800200, v108
	v_mul_f32_e32 v109, 0xb8800200, v109
	v_mul_f32_e32 v110, 0xb8800200, v110
	v_mul_f32_e32 v111, 0xb8800200, v111
	v_mul_f32_e64 v108, |v11|, v108
	v_mul_f32_e64 v109, |v11|, v109
	v_mul_f32_e64 v110, |v11|, v110
	v_mul_f32_e64 v111, |v11|, v111
	v_mul_f32_e32 v108, 0x3fb8aa3b, v108
	v_mul_f32_e32 v109, 0x3fb8aa3b, v109
	v_mul_f32_e32 v110, 0x3fb8aa3b, v110
	v_mul_f32_e32 v111, 0x3fb8aa3b, v111
	v_mfma_f32_16x16x32_bf16 v[88:91], v[88:91], v[64:67], 0
	v_mfma_f32_16x16x32_bf16 v[88:91], v[92:95], v[68:71], v[88:91]
	v_exp_f32_e32 v104, v108
	v_exp_f32_e32 v105, v109
	v_exp_f32_e32 v106, v110
	v_exp_f32_e32 v107, v111
	s_nop 7
	v_pk_mul_f32 v[90:91], v[90:91], v[106:107]
	v_pk_mul_f32 v[88:89], v[88:89], v[104:105]
	global_store_dwordx4 v9, v[88:91], s[18:19] offset:896
	v_add_u32_e32 v108, 240, v12
	v_add_u32_e32 v109, 241, v12
	v_add_u32_e32 v110, 242, v12
	v_add_u32_e32 v111, 243, v12
	v_cvt_f32_i32_e32 v108, v108
	v_cvt_f32_i32_e32 v109, v109
	v_cvt_f32_i32_e32 v110, v110
	v_cvt_f32_i32_e32 v111, v111
	v_mul_f32_e32 v108, 0xb8800200, v108
	v_mul_f32_e32 v109, 0xb8800200, v109
	v_mul_f32_e32 v110, 0xb8800200, v110
	v_mul_f32_e32 v111, 0xb8800200, v111
	v_mul_f32_e64 v108, |v11|, v108
	v_mul_f32_e64 v109, |v11|, v109
	v_mul_f32_e64 v110, |v11|, v110
	v_mul_f32_e64 v111, |v11|, v111
	v_mul_f32_e32 v108, 0x3fb8aa3b, v108
	v_mul_f32_e32 v109, 0x3fb8aa3b, v109
	v_mul_f32_e32 v110, 0x3fb8aa3b, v110
	v_mul_f32_e32 v111, 0x3fb8aa3b, v111
	v_mfma_f32_16x16x32_bf16 v[96:99], v[96:99], v[64:67], 0
	v_mfma_f32_16x16x32_bf16 v[96:99], v[100:103], v[68:71], v[96:99]
	v_exp_f32_e32 v104, v108
	v_exp_f32_e32 v105, v109
	v_exp_f32_e32 v106, v110
	v_exp_f32_e32 v107, v111
	s_nop 7
	v_pk_mul_f32 v[98:99], v[98:99], v[106:107]
	v_pk_mul_f32 v[96:97], v[96:97], v[104:105]
	global_store_dwordx4 v9, v[96:99], s[18:19] offset:960
	s_add_u32 s3, s3, s7
	s_cmp_lt_i32 s3, s14
	s_cbranch_scc1 .Lfg_id
.Lfg_done:
	s_mov_b64 s[4:5], exec
